# Wd2 copy moved to P9 last-round idle WGs; P0 GEMV 16 rows per iteration; P0 transposes only Wgu1
# speedup vs baseline: 1.0069x; 1.0006x over previous
.LBB0_22:
	s_mul_hi_i32 s4, s19, 0x66666667
	s_lshr_b32 s5, s4, 31
	s_ashr_i32 s22, s4, 4
	s_add_i32 s22, s22, s5
	s_mul_i32 s4, s22, 0x28
	s_lshl_b32 s6, s22, 7
	v_readlane_b32 s36, v241, 5
	s_sub_i32 s4, s19, s4
	s_ashr_i32 s7, s6, 31
	s_mul_i32 s5, s22, 0x900000
	v_readlane_b32 s40, v241, 9
	s_mul_hi_i32 s8, s6, 0x12000
	v_readlane_b32 s41, v241, 10
	s_add_u32 s9, s40, s5
	s_addc_u32 s23, s41, s8
	s_lshl_b32 s4, s4, 8
	s_ashr_i32 s5, s4, 31
	s_lshl_b64 s[4:5], s[4:5], 2
	s_add_u32 s8, s9, s4
	s_addc_u32 s9, s23, s5
	s_lshl_b64 s[6:7], s[6:7], 2
	s_add_u32 s6, s10, s6
	v_lshl_add_u64 v[8:9], s[8:9], 0, v[6:7]
	s_addc_u32 s7, s11, s7
	s_mov_b64 s[8:9], 0
	v_mov_b32_e32 v2, 0
	v_mov_b32_e32 v3, v7
	v_mov_b32_e32 v4, 0
	v_mov_b32_e32 v5, v7
	v_readlane_b32 s37, v241, 6
	v_readlane_b32 s38, v241, 7
	v_readlane_b32 s39, v241, 8
	v_readlane_b32 s42, v241, 11
	v_readlane_b32 s43, v241, 12
	v_readlane_b32 s44, v241, 13
	v_readlane_b32 s45, v241, 14
	v_readlane_b32 s46, v241, 15
	v_readlane_b32 s47, v241, 16
	v_readlane_b32 s48, v241, 17
	v_readlane_b32 s49, v241, 18
	v_readlane_b32 s50, v241, 19
	v_readlane_b32 s51, v241, 20
	v_mov_b32_e32 v106, v8
	v_mov_b32_e32 v107, v9
	s_mov_b32 s100, 0x12000
	s_mov_b32 s101, 0
	s_mov_b32 s8, 8
.LBB0_23:
	global_load_dwordx4 v[10:13], v7, s[6:7] offset:-28
	global_load_dwordx4 v[14:17], v7, s[6:7] offset:-12
	global_load_dwordx4 v[18:21], v7, s[6:7] offset:4
	global_load_dwordx4 v[22:25], v7, s[6:7] offset:20
	global_load_dwordx4 v[26:29], v[106:107], off nt
	v_lshl_add_u64 v[106:107], v[106:107], 0, s[100:101]
	global_load_dwordx4 v[30:33], v[106:107], off nt
	v_lshl_add_u64 v[106:107], v[106:107], 0, s[100:101]
	global_load_dwordx4 v[34:37], v[106:107], off nt
	v_lshl_add_u64 v[106:107], v[106:107], 0, s[100:101]
	global_load_dwordx4 v[38:41], v[106:107], off nt
	v_lshl_add_u64 v[106:107], v[106:107], 0, s[100:101]
	global_load_dwordx4 v[42:45], v[106:107], off nt
	v_lshl_add_u64 v[106:107], v[106:107], 0, s[100:101]
	global_load_dwordx4 v[46:49], v[106:107], off nt
	v_lshl_add_u64 v[106:107], v[106:107], 0, s[100:101]
	global_load_dwordx4 v[50:53], v[106:107], off nt
	v_lshl_add_u64 v[106:107], v[106:107], 0, s[100:101]
	global_load_dwordx4 v[54:57], v[106:107], off nt
	v_lshl_add_u64 v[106:107], v[106:107], 0, s[100:101]
	global_load_dwordx4 v[58:61], v[106:107], off nt
	v_lshl_add_u64 v[106:107], v[106:107], 0, s[100:101]
	global_load_dwordx4 v[62:65], v[106:107], off nt
	v_lshl_add_u64 v[106:107], v[106:107], 0, s[100:101]
	global_load_dwordx4 v[66:69], v[106:107], off nt
	v_lshl_add_u64 v[106:107], v[106:107], 0, s[100:101]
	global_load_dwordx4 v[70:73], v[106:107], off nt
	v_lshl_add_u64 v[106:107], v[106:107], 0, s[100:101]
	global_load_dwordx4 v[74:77], v[106:107], off nt
	v_lshl_add_u64 v[106:107], v[106:107], 0, s[100:101]
	global_load_dwordx4 v[78:81], v[106:107], off nt
	v_lshl_add_u64 v[106:107], v[106:107], 0, s[100:101]
	global_load_dwordx4 v[82:85], v[106:107], off nt
	v_lshl_add_u64 v[106:107], v[106:107], 0, s[100:101]
	global_load_dwordx4 v[86:89], v[106:107], off nt
	v_lshl_add_u64 v[106:107], v[106:107], 0, s[100:101]
	s_add_u32 s6, s6, 64
	s_addc_u32 s7, s7, 0
	s_waitcnt vmcnt(16)
	v_mul_f32_e32 v90, 0xbfb8aa3b, v10
	v_mul_f32_e32 v91, 0xbfb8aa3b, v11
	v_mul_f32_e32 v92, 0xbfb8aa3b, v12
	v_mul_f32_e32 v93, 0xbfb8aa3b, v13
	v_mul_f32_e32 v94, 0xbfb8aa3b, v14
	v_mul_f32_e32 v95, 0xbfb8aa3b, v15
	v_mul_f32_e32 v96, 0xbfb8aa3b, v16
	v_mul_f32_e32 v97, 0xbfb8aa3b, v17
	v_mul_f32_e32 v98, 0xbfb8aa3b, v18
	v_mul_f32_e32 v99, 0xbfb8aa3b, v19
	v_mul_f32_e32 v100, 0xbfb8aa3b, v20
	v_mul_f32_e32 v101, 0xbfb8aa3b, v21
	v_mul_f32_e32 v102, 0xbfb8aa3b, v22
	v_mul_f32_e32 v103, 0xbfb8aa3b, v23
	v_mul_f32_e32 v104, 0xbfb8aa3b, v24
	v_mul_f32_e32 v105, 0xbfb8aa3b, v25
	v_exp_f32_e32 v90, v90
	v_exp_f32_e32 v91, v91
	v_exp_f32_e32 v92, v92
	v_exp_f32_e32 v93, v93
	v_exp_f32_e32 v94, v94
	v_exp_f32_e32 v95, v95
	v_exp_f32_e32 v96, v96
	v_exp_f32_e32 v97, v97
	v_exp_f32_e32 v98, v98
	v_exp_f32_e32 v99, v99
	v_exp_f32_e32 v100, v100
	v_exp_f32_e32 v101, v101
	v_exp_f32_e32 v102, v102
	v_exp_f32_e32 v103, v103
	v_exp_f32_e32 v104, v104
	v_exp_f32_e32 v105, v105
	v_add_f32_e32 v90, 1.0, v90
	v_add_f32_e32 v91, 1.0, v91
	v_add_f32_e32 v92, 1.0, v92
	v_add_f32_e32 v93, 1.0, v93
	v_add_f32_e32 v94, 1.0, v94
	v_add_f32_e32 v95, 1.0, v95
	v_add_f32_e32 v96, 1.0, v96
	v_add_f32_e32 v97, 1.0, v97
	v_add_f32_e32 v98, 1.0, v98
	v_add_f32_e32 v99, 1.0, v99
	v_add_f32_e32 v100, 1.0, v100
	v_add_f32_e32 v101, 1.0, v101
	v_add_f32_e32 v102, 1.0, v102
	v_add_f32_e32 v103, 1.0, v103
	v_add_f32_e32 v104, 1.0, v104
	v_add_f32_e32 v105, 1.0, v105
	v_rcp_f32_e32 v90, v90
	v_rcp_f32_e32 v91, v91
	v_rcp_f32_e32 v92, v92
	v_rcp_f32_e32 v93, v93
	v_rcp_f32_e32 v94, v94
	v_rcp_f32_e32 v95, v95
	v_rcp_f32_e32 v96, v96
	v_rcp_f32_e32 v97, v97
	v_rcp_f32_e32 v98, v98
	v_rcp_f32_e32 v99, v99
	v_rcp_f32_e32 v100, v100
	v_rcp_f32_e32 v101, v101
	v_rcp_f32_e32 v102, v102
	v_rcp_f32_e32 v103, v103
	v_rcp_f32_e32 v104, v104
	v_rcp_f32_e32 v105, v105
	v_mul_f32_e32 v10, v10, v90
	v_mul_f32_e32 v11, v11, v91
	v_mul_f32_e32 v12, v12, v92
	v_mul_f32_e32 v13, v13, v93
	v_mul_f32_e32 v14, v14, v94
	v_mul_f32_e32 v15, v15, v95
	v_mul_f32_e32 v16, v16, v96
	v_mul_f32_e32 v17, v17, v97
	v_mul_f32_e32 v18, v18, v98
	v_mul_f32_e32 v19, v19, v99
	v_mul_f32_e32 v20, v20, v100
	v_mul_f32_e32 v21, v21, v101
	v_mul_f32_e32 v22, v22, v102
	v_mul_f32_e32 v23, v23, v103
	v_mul_f32_e32 v24, v24, v104
	v_mul_f32_e32 v25, v25, v105
	s_waitcnt vmcnt(15)
	v_pk_fma_f32 v[4:5], v[28:29], v[10:11], v[4:5] op_sel_hi:[1,0,1]
	v_pk_fma_f32 v[2:3], v[26:27], v[10:11], v[2:3] op_sel_hi:[1,0,1]
	s_waitcnt vmcnt(14)
	v_pk_fma_f32 v[4:5], v[32:33], v[10:11], v[4:5] op_sel:[0,1,0] op_sel_hi:[1,1,1]
	v_pk_fma_f32 v[2:3], v[30:31], v[10:11], v[2:3] op_sel:[0,1,0] op_sel_hi:[1,1,1]
	s_waitcnt vmcnt(13)
	v_pk_fma_f32 v[4:5], v[36:37], v[12:13], v[4:5] op_sel_hi:[1,0,1]
	v_pk_fma_f32 v[2:3], v[34:35], v[12:13], v[2:3] op_sel_hi:[1,0,1]
	s_waitcnt vmcnt(12)
	v_pk_fma_f32 v[4:5], v[40:41], v[12:13], v[4:5] op_sel:[0,1,0] op_sel_hi:[1,1,1]
	v_pk_fma_f32 v[2:3], v[38:39], v[12:13], v[2:3] op_sel:[0,1,0] op_sel_hi:[1,1,1]
	s_waitcnt vmcnt(11)
	v_pk_fma_f32 v[4:5], v[44:45], v[14:15], v[4:5] op_sel_hi:[1,0,1]
	v_pk_fma_f32 v[2:3], v[42:43], v[14:15], v[2:3] op_sel_hi:[1,0,1]
	s_waitcnt vmcnt(10)
	v_pk_fma_f32 v[4:5], v[48:49], v[14:15], v[4:5] op_sel:[0,1,0] op_sel_hi:[1,1,1]
	v_pk_fma_f32 v[2:3], v[46:47], v[14:15], v[2:3] op_sel:[0,1,0] op_sel_hi:[1,1,1]
	s_waitcnt vmcnt(9)
	v_pk_fma_f32 v[4:5], v[52:53], v[16:17], v[4:5] op_sel_hi:[1,0,1]
	v_pk_fma_f32 v[2:3], v[50:51], v[16:17], v[2:3] op_sel_hi:[1,0,1]
	s_waitcnt vmcnt(8)
	v_pk_fma_f32 v[4:5], v[56:57], v[16:17], v[4:5] op_sel:[0,1,0] op_sel_hi:[1,1,1]
	v_pk_fma_f32 v[2:3], v[54:55], v[16:17], v[2:3] op_sel:[0,1,0] op_sel_hi:[1,1,1]
	s_waitcnt vmcnt(7)
	v_pk_fma_f32 v[4:5], v[60:61], v[18:19], v[4:5] op_sel_hi:[1,0,1]
	v_pk_fma_f32 v[2:3], v[58:59], v[18:19], v[2:3] op_sel_hi:[1,0,1]
	s_waitcnt vmcnt(6)
	v_pk_fma_f32 v[4:5], v[64:65], v[18:19], v[4:5] op_sel:[0,1,0] op_sel_hi:[1,1,1]
	v_pk_fma_f32 v[2:3], v[62:63], v[18:19], v[2:3] op_sel:[0,1,0] op_sel_hi:[1,1,1]
	s_waitcnt vmcnt(5)
	v_pk_fma_f32 v[4:5], v[68:69], v[20:21], v[4:5] op_sel_hi:[1,0,1]
	v_pk_fma_f32 v[2:3], v[66:67], v[20:21], v[2:3] op_sel_hi:[1,0,1]
	s_waitcnt vmcnt(4)
	v_pk_fma_f32 v[4:5], v[72:73], v[20:21], v[4:5] op_sel:[0,1,0] op_sel_hi:[1,1,1]
	v_pk_fma_f32 v[2:3], v[70:71], v[20:21], v[2:3] op_sel:[0,1,0] op_sel_hi:[1,1,1]
	s_waitcnt vmcnt(3)
	v_pk_fma_f32 v[4:5], v[76:77], v[22:23], v[4:5] op_sel_hi:[1,0,1]
	v_pk_fma_f32 v[2:3], v[74:75], v[22:23], v[2:3] op_sel_hi:[1,0,1]
	s_waitcnt vmcnt(2)
	v_pk_fma_f32 v[4:5], v[80:81], v[22:23], v[4:5] op_sel:[0,1,0] op_sel_hi:[1,1,1]
	v_pk_fma_f32 v[2:3], v[78:79], v[22:23], v[2:3] op_sel:[0,1,0] op_sel_hi:[1,1,1]
	s_waitcnt vmcnt(1)
	v_pk_fma_f32 v[4:5], v[84:85], v[24:25], v[4:5] op_sel_hi:[1,0,1]
	v_pk_fma_f32 v[2:3], v[82:83], v[24:25], v[2:3] op_sel_hi:[1,0,1]
	s_waitcnt vmcnt(0)
	v_pk_fma_f32 v[4:5], v[88:89], v[24:25], v[4:5] op_sel:[0,1,0] op_sel_hi:[1,1,1]
	v_pk_fma_f32 v[2:3], v[86:87], v[24:25], v[2:3] op_sel:[0,1,0] op_sel_hi:[1,1,1]
	s_sub_u32 s8, s8, 1
	s_cmp_lg_u32 s8, 0
	s_cbranch_scc1 .LBB0_23
	s_mul_hi_i32 s6, s22, 0x12000
	s_mul_i32 s22, s22, 0x12000
	s_add_u32 s7, s0, s22
	s_addc_u32 s6, s1, s6
	s_add_u32 s4, s7, s4
	s_addc_u32 s5, s6, s5
	s_add_i32 s19, s19, s86
	s_cmpk_gt_i32 s19, 0x27f
	global_store_dwordx4 v6, v[2:5], s[4:5]
	s_cbranch_scc0 .LBB0_22
.LBB0_25:
	v_readlane_b32 s4, v241, 0
	s_cmpk_eq_i32 s4, 0x100
	s_movk_i32 s4, 0x2c00
	s_cselect_b32 s14, s4, 0x8200
	s_mov_b32 s98, s96
	s_mov_b32 s99, s86
	v_readlane_b32 s5, v241, 0
	s_nop 3
	s_cmpk_lg_i32 s5, 0x100
	s_cbranch_scc1 .Lp0bal_go
	s_sub_i32 s98, s96, 0x280
	s_cmp_lt_i32 s98, 0
	s_cbranch_scc1 .LBB0_40
	s_sub_i32 s99, s86, 0x280

.LBB0_160:
	s_cmp_lt_i32 s90, 3
	s_cselect_b64 s[2:3], -1, 0
	s_add_u32 s44, s94, 0xa400000
	s_addc_u32 s45, s95, 0
	s_add_u32 s4, s94, 0xc400000
	s_addc_u32 s5, s95, 0
	v_writelane_b32 v241, s4, 56
	s_and_b64 s[2:3], s[2:3], s[0:1]
	s_andn2_b64 vcc, exec, s[2:3]
	v_writelane_b32 v241, s5, 57
	v_writelane_b32 v241, s44, 58
	v_writelane_b32 v241, s45, 59
	s_cbranch_vccnz .LBB0_196
	v_readlane_b32 s0, v241, 0
	s_cmpk_lg_i32 s0, 0x100
	v_readlane_b32 s1, v241, 1
	s_cselect_b32 s33, s0, 0xf0
	s_cmp_ge_i32 s72, s33
	s_mov_b64 s[0:1], -1
	s_cbranch_scc0 .LBB0_178
	s_sub_i32 s0, s72, s33
	s_lshl_b32 s0, s0, 3
	s_add_i32 s0, s0, s20
	s_cmpk_gt_u32 s0, 0x35ff
	s_cbranch_scc1 .LBB0_177
	s_add_i32 s13, s0, 0x2c00
	s_lshl_b32 s0, s20, 14
	s_addk_i32 s0, 0x100
	v_lshrrev_b32_e32 v1, 5, v147
	v_and_b32_e32 v2, 31, v146
	v_lshlrev_b32_e32 v4, 3, v146
	v_readlane_b32 s4, v241, 0
	v_lshl_add_u32 v7, v2, 2, s0
	v_mul_u32_u24_e32 v13, 0x84, v1
	v_lshrrev_b32_e32 v8, 3, v147
	v_and_b32_e32 v6, 56, v4
	s_sub_i32 s1, s4, s33
	v_mov_b32_e32 v3, 0
	v_mul_u32_u24_e32 v4, 0x84, v6
	v_lshlrev_b32_e32 v5, 2, v8
	v_add_u32_e32 v13, v7, v13
	s_lshl_b32 s12, s1, 3
	v_add3_u32 v9, s0, v4, v5
	v_or_b32_e32 v10, 8, v8
	v_or_b32_e32 v11, 16, v8
	v_or_b32_e32 v12, 24, v8
	s_lshl_b32 s14, s13, 5
	s_lshl_b32 s15, s1, 8
	s_lshl_b32 s16, s13, 4
	s_lshl_b32 s17, s1, 7
	v_lshlrev_b32_e32 v4, 2, v2
	v_mov_b32_e32 v5, v3
	v_lshlrev_b32_e32 v6, 1, v6
	v_mov_b32_e32 v7, v3
	v_add_u32_e32 v14, 0x400, v13
	v_add_u32_e32 v15, 0x800, v13
	v_add_u32_e32 v16, 0xc00, v13
	v_add_u32_e32 v17, 0x1000, v13
	v_add_u32_e32 v18, 0x1400, v13
	v_add_u32_e32 v19, 0x1800, v13
	v_add_u32_e32 v20, 0x1c00, v13
	v_readlane_b32 s5, v241, 1
	s_branch .LBB0_165

.LBB0_484:
	v_readlane_b32 s0, v241, 0
	s_min_i32 s2, s0, 0x80
	v_readlane_b32 s1, v241, 1
	s_cmpk_gt_i32 s0, 0x80
	s_cselect_b64 s[0:1], -1, 0
	s_cmp_lt_i32 s72, s2
	s_cselect_b64 s[4:5], -1, 0
	s_and_b64 s[4:5], s[0:1], s[4:5]
	s_and_b64 vcc, exec, s[4:5]
	s_cbranch_vccnz .LBB0_493
	s_sub_i32 s3, s72, s2
	s_lshl_b32 s3, s3, 3
	s_add_i32 s3, s3, s20
	s_and_b64 s[4:5], s[0:1], exec
	s_cselect_b32 s6, s3, s96
	s_cmpk_gt_i32 s6, 0x7ff
	v_readlane_b32 s22, v241, 60
	v_readlane_b32 s23, v241, 61
	s_cbranch_scc1 .LBB0_492
	v_readlane_b32 s4, v241, 0
	s_sub_i32 s2, s4, s2
	s_lshl_b32 s2, s2, 3
	s_and_b64 s[0:1], s[0:1], exec
	s_cselect_b32 s7, s2, s86
	s_lshl_b32 s0, s20, 14
	s_addk_i32 s0, 0x100
	v_lshrrev_b32_e32 v1, 5, v147
	v_and_b32_e32 v6, 31, v146
	v_lshlrev_b32_e32 v4, 3, v146
	v_lshlrev_b32_e32 v2, 11, v1
	v_lshl_add_u32 v9, v6, 2, s0
	v_mul_u32_u24_e32 v14, 0x84, v1
	v_lshrrev_b32_e32 v1, 3, v147
	v_and_b32_e32 v8, 56, v4
	v_mov_b32_e32 v3, 0
	v_mul_u32_u24_e32 v4, 0x84, v8
	v_lshlrev_b32_e32 v5, 2, v1
	v_add_u32_e32 v14, v9, v14
	v_add3_u32 v10, s0, v4, v5
	v_or_b32_e32 v11, 8, v1
	v_or_b32_e32 v12, 16, v1
	v_or_b32_e32 v13, 24, v1
	s_lshl_b32 s12, s6, 5
	s_lshl_b32 s13, s7, 5
	v_lshlrev_b32_e32 v4, 2, v2
	v_mov_b32_e32 v5, v3
	v_lshlrev_b32_e32 v6, 2, v6
	v_mov_b32_e32 v7, v3
	v_lshlrev_b32_e32 v8, 1, v8
	v_mov_b32_e32 v9, v3
	v_add_u32_e32 v15, 0x400, v14
	v_add_u32_e32 v16, 0x800, v14
	v_add_u32_e32 v17, 0xc00, v14
	v_add_u32_e32 v18, 0x1000, v14
	v_add_u32_e32 v19, 0x1400, v14
	v_add_u32_e32 v20, 0x1800, v14
	v_add_u32_e32 v21, 0x1c00, v14
	v_readlane_b32 s5, v241, 1
	s_branch .LBB0_488
.LBB0_487:
	v_lshl_add_u64 v[22:23], s[4:5], 0, v[4:5]
	v_lshl_add_u64 v[22:23], v[22:23], 0, v[6:7]
	v_add_co_u32_e32 v24, vcc, 0x4000, v22
	s_add_i32 s6, s6, s7
	s_nop 0
	v_addc_co_u32_e32 v25, vcc, 0, v23, vcc
	v_add_co_u32_e32 v26, vcc, 0x8000, v22
	s_add_i32 s12, s12, s13
	s_nop 0
	v_addc_co_u32_e32 v27, vcc, 0, v23, vcc
	v_add_co_u32_e32 v28, vcc, 0xc000, v22
	s_cmpk_lt_i32 s6, 0x800
	s_nop 0
	v_addc_co_u32_e32 v29, vcc, 0, v23, vcc
	v_add_co_u32_e32 v30, vcc, 0x10000, v22
	s_nop 1
	v_addc_co_u32_e32 v31, vcc, 0, v23, vcc
	v_add_co_u32_e32 v32, vcc, 0x14000, v22
	s_nop 1
	v_addc_co_u32_e32 v33, vcc, 0, v23, vcc
	v_add_co_u32_e32 v34, vcc, 0x18000, v22
	s_nop 1
	v_addc_co_u32_e32 v35, vcc, 0, v23, vcc
	v_add_co_u32_e32 v36, vcc, 0x1c000, v22
	s_nop 1
	v_addc_co_u32_e32 v37, vcc, 0, v23, vcc
	global_load_dword v2, v[22:23], off nt
	global_load_dword v40, v[24:25], off nt
	global_load_dword v41, v[26:27], off nt
	global_load_dword v42, v[28:29], off nt
	global_load_dword v43, v[30:31], off nt
	global_load_dword v44, v[32:33], off nt
	global_load_dword v45, v[34:35], off nt
	global_load_dword v46, v[36:37], off nt
	v_add_co_u32_e32 v24, vcc, 0x20000, v22
	s_nop 1
	v_addc_co_u32_e32 v25, vcc, 0, v23, vcc
	v_add_co_u32_e32 v26, vcc, 0x24000, v22
	s_nop 1
	v_addc_co_u32_e32 v27, vcc, 0, v23, vcc
	v_add_co_u32_e32 v28, vcc, 0x28000, v22
	s_nop 1
	v_addc_co_u32_e32 v29, vcc, 0, v23, vcc
	v_add_co_u32_e32 v30, vcc, 0x2c000, v22
	s_nop 1
	v_addc_co_u32_e32 v31, vcc, 0, v23, vcc
	v_add_co_u32_e32 v32, vcc, 0x30000, v22
	s_nop 1
	v_addc_co_u32_e32 v33, vcc, 0, v23, vcc
	v_add_co_u32_e32 v34, vcc, 0x34000, v22
	s_nop 1
	v_addc_co_u32_e32 v35, vcc, 0, v23, vcc
	v_add_co_u32_e32 v36, vcc, 0x38000, v22
	s_nop 1
	v_addc_co_u32_e32 v37, vcc, 0, v23, vcc
	v_add_co_u32_e32 v38, vcc, 0x3c000, v22
	s_nop 1
	v_addc_co_u32_e32 v39, vcc, 0, v23, vcc
	global_load_dword v47, v[24:25], off nt
	global_load_dword v48, v[26:27], off nt
	global_load_dword v49, v[28:29], off nt
	global_load_dword v50, v[30:31], off nt
	global_load_dword v51, v[32:33], off nt
	global_load_dword v52, v[34:35], off nt
	global_load_dword v53, v[36:37], off nt
	global_load_dword v54, v[38:39], off nt
	v_add_co_u32_e32 v24, vcc, 0x40000, v22
	s_nop 1
	v_addc_co_u32_e32 v25, vcc, 0, v23, vcc
	v_add_co_u32_e32 v26, vcc, 0x44000, v22
	s_nop 1
	v_addc_co_u32_e32 v27, vcc, 0, v23, vcc
	v_add_co_u32_e32 v28, vcc, 0x48000, v22
	s_nop 1
	v_addc_co_u32_e32 v29, vcc, 0, v23, vcc
	v_add_co_u32_e32 v30, vcc, 0x4c000, v22
	s_nop 1
	v_addc_co_u32_e32 v31, vcc, 0, v23, vcc
	v_add_co_u32_e32 v32, vcc, 0x50000, v22
	s_nop 1
	v_addc_co_u32_e32 v33, vcc, 0, v23, vcc
	v_add_co_u32_e32 v34, vcc, 0x54000, v22
	s_nop 1
	v_addc_co_u32_e32 v35, vcc, 0, v23, vcc
	v_add_co_u32_e32 v36, vcc, 0x58000, v22
	s_nop 1
	v_addc_co_u32_e32 v37, vcc, 0, v23, vcc
	v_add_co_u32_e32 v38, vcc, 0x5c000, v22
	s_nop 1
	v_addc_co_u32_e32 v39, vcc, 0, v23, vcc
	global_load_dword v55, v[24:25], off nt
	global_load_dword v56, v[26:27], off nt
	global_load_dword v57, v[28:29], off nt
	global_load_dword v58, v[30:31], off nt
	global_load_dword v59, v[32:33], off nt
	global_load_dword v60, v[34:35], off nt
	global_load_dword v61, v[36:37], off nt
	s_nop 0
	global_load_dword v38, v[38:39], off nt
	v_add_co_u32_e32 v24, vcc, 0x60000, v22
	s_nop 1
	v_addc_co_u32_e32 v25, vcc, 0, v23, vcc
	v_add_co_u32_e32 v26, vcc, 0x64000, v22
	s_nop 1
	v_addc_co_u32_e32 v27, vcc, 0, v23, vcc
	v_add_co_u32_e32 v28, vcc, 0x68000, v22
	s_nop 1
	v_addc_co_u32_e32 v29, vcc, 0, v23, vcc
	v_add_co_u32_e32 v30, vcc, 0x6c000, v22
	s_nop 1
	v_addc_co_u32_e32 v31, vcc, 0, v23, vcc
	v_add_co_u32_e32 v32, vcc, 0x70000, v22
	s_nop 1
	v_addc_co_u32_e32 v33, vcc, 0, v23, vcc
	v_add_co_u32_e32 v34, vcc, 0x74000, v22
	s_nop 1
	v_addc_co_u32_e32 v35, vcc, 0, v23, vcc
	v_add_co_u32_e32 v36, vcc, 0x78000, v22
	s_nop 1
	v_addc_co_u32_e32 v37, vcc, 0, v23, vcc
	v_add_co_u32_e32 v22, vcc, 0x7c000, v22
	s_nop 1
	v_addc_co_u32_e32 v23, vcc, 0, v23, vcc
	global_load_dword v24, v[24:25], off nt
	s_nop 0
	global_load_dword v25, v[26:27], off nt
	s_nop 0
	global_load_dword v26, v[28:29], off nt
	global_load_dword v27, v[30:31], off nt
	s_nop 0
	global_load_dword v28, v[32:33], off nt
	global_load_dword v29, v[34:35], off nt
	global_load_dword v30, v[36:37], off nt
	s_nop 0
	global_load_dword v22, v[22:23], off nt
	s_waitcnt vmcnt(0)
	ds_write2_b32 v14, v2, v40 offset1:66
	ds_write2_b32 v14, v41, v42 offset0:132 offset1:198
	ds_write2_b32 v15, v43, v44 offset0:8 offset1:74
	ds_write2_b32 v15, v45, v46 offset0:140 offset1:206
	ds_write2_b32 v16, v47, v48 offset0:16 offset1:82
	ds_write2_b32 v16, v49, v50 offset0:148 offset1:214
	ds_write2_b32 v17, v51, v52 offset0:24 offset1:90
	ds_write2_b32 v17, v53, v54 offset0:156 offset1:222
	ds_write2_b32 v18, v55, v56 offset0:32 offset1:98
	ds_write2_b32 v18, v57, v58 offset0:164 offset1:230
	ds_write2_b32 v19, v59, v60 offset0:40 offset1:106
	ds_write2_b32 v19, v61, v38 offset0:172 offset1:238
	ds_write2_b32 v20, v24, v25 offset0:48 offset1:114
	ds_write2_b32 v20, v26, v27 offset0:180 offset1:246
	ds_write2_b32 v21, v28, v29 offset0:56 offset1:122
	ds_write2_b32 v21, v30, v22 offset0:188 offset1:254
	s_waitcnt lgkmcnt(0)
	ds_read2_b32 v[22:23], v10 offset1:33
	s_waitcnt lgkmcnt(0)
	v_cvt_pk_bf16_f32 v22, v22, v23
	ds_read2_b32 v[24:25], v10 offset0:66 offset1:99
	v_mul_u32_u24_e32 v2, s0, v1
	s_waitcnt lgkmcnt(0)
	v_cvt_pk_bf16_f32 v23, v24, v25
	ds_read2_b32 v[24:25], v10 offset0:132 offset1:165
	v_lshl_add_u64 v[28:29], s[2:3], 0, v[8:9]
	v_lshlrev_b32_e32 v2, 1, v2
	s_waitcnt lgkmcnt(0)
	v_cvt_pk_bf16_f32 v24, v24, v25
	ds_read2_b32 v[26:27], v10 offset0:198 offset1:231
	s_waitcnt lgkmcnt(0)
	v_cvt_pk_bf16_f32 v25, v26, v27
	v_lshl_add_u64 v[30:31], v[28:29], 0, v[2:3]
	ds_read2_b32 v[26:27], v10 offset0:8 offset1:41
	global_store_dwordx4 v[30:31], v[22:25], off
	v_mul_u32_u24_e32 v2, s0, v11
	v_lshlrev_b32_e32 v2, 1, v2
	s_waitcnt lgkmcnt(0)
	v_cvt_pk_bf16_f32 v22, v26, v27
	ds_read2_b32 v[24:25], v10 offset0:74 offset1:107
	s_waitcnt lgkmcnt(0)
	v_cvt_pk_bf16_f32 v23, v24, v25
	ds_read2_b32 v[24:25], v10 offset0:140 offset1:173
	s_waitcnt lgkmcnt(0)
	v_cvt_pk_bf16_f32 v24, v24, v25
	ds_read2_b32 v[26:27], v10 offset0:206 offset1:239
	s_waitcnt lgkmcnt(0)
	v_cvt_pk_bf16_f32 v25, v26, v27
	v_lshl_add_u64 v[30:31], v[28:29], 0, v[2:3]
	ds_read2_b32 v[26:27], v10 offset0:16 offset1:49
	global_store_dwordx4 v[30:31], v[22:25], off
	v_mul_u32_u24_e32 v2, s0, v12
	v_lshlrev_b32_e32 v2, 1, v2
	s_waitcnt lgkmcnt(0)
	v_cvt_pk_bf16_f32 v22, v26, v27
	ds_read2_b32 v[24:25], v10 offset0:82 offset1:115
	s_waitcnt lgkmcnt(0)
	v_cvt_pk_bf16_f32 v23, v24, v25
	ds_read2_b32 v[24:25], v10 offset0:148 offset1:181
	s_waitcnt lgkmcnt(0)
	v_cvt_pk_bf16_f32 v24, v24, v25
	ds_read2_b32 v[26:27], v10 offset0:214 offset1:247
	s_waitcnt lgkmcnt(0)
	v_cvt_pk_bf16_f32 v25, v26, v27
	v_lshl_add_u64 v[30:31], v[28:29], 0, v[2:3]
	ds_read2_b32 v[26:27], v10 offset0:24 offset1:57
	global_store_dwordx4 v[30:31], v[22:25], off
	v_mul_u32_u24_e32 v2, s0, v13
	v_lshlrev_b32_e32 v2, 1, v2
	s_waitcnt lgkmcnt(0)
	v_cvt_pk_bf16_f32 v22, v26, v27
	ds_read2_b32 v[24:25], v10 offset0:90 offset1:123
	s_waitcnt lgkmcnt(0)
	v_cvt_pk_bf16_f32 v23, v24, v25
	ds_read2_b32 v[24:25], v10 offset0:156 offset1:189
	s_waitcnt lgkmcnt(0)
	v_cvt_pk_bf16_f32 v24, v24, v25
	ds_read2_b32 v[26:27], v10 offset0:222 offset1:255
	s_waitcnt lgkmcnt(0)
	v_cvt_pk_bf16_f32 v25, v26, v27
	v_lshl_add_u64 v[26:27], v[28:29], 0, v[2:3]
	global_store_dwordx4 v[26:27], v[22:25], off
	s_waitcnt lgkmcnt(0)
	s_cbranch_scc0 .LBB0_492

.LBB0_833:
	s_waitcnt vmcnt(0)
	v_readlane_b32 s33, v241, 55
	s_barrier
	v_readlane_b32 s0, v241, 0
	s_nop 3
	s_cmpk_lg_i32 s0, 0x100
	s_cbranch_scc1 .Lp9x_done
	s_cmpk_lt_i32 s72, 0x80
	s_cbranch_scc1 .Lp9x_done
	s_mov_b32 s98, s2
	s_mov_b32 s99, s3
	s_mov_b32 s100, s23
	v_readfirstlane_b32 s11, v146
	s_nop 3
	s_lshr_b32 s11, s11, 6
	s_sub_i32 s6, s72, 0x80
	s_lshl_b32 s6, s6, 3
	s_add_i32 s6, s6, s11
	s_addk_i32 s6, 0x800
	s_cmpk_gt_i32 s6, 0x1dff
	s_cbranch_scc1 .Lp9x_restore
	s_movk_i32 s7, 0x400
	v_readlane_b32 s22, v241, 60
	v_readlane_b32 s23, v241, 61
	s_lshl_b32 s0, s11, 14
	s_addk_i32 s0, 0x100
	v_lshrrev_b32_e32 v1, 5, v147
	v_and_b32_e32 v6, 31, v146
	v_lshlrev_b32_e32 v4, 3, v146
	v_lshlrev_b32_e32 v2, 11, v1
	v_lshl_add_u32 v9, v6, 2, s0
	v_mul_u32_u24_e32 v14, 0x84, v1
	v_lshrrev_b32_e32 v1, 3, v147
	v_and_b32_e32 v8, 56, v4
	v_mov_b32_e32 v3, 0
	v_mul_u32_u24_e32 v4, 0x84, v8
	v_lshlrev_b32_e32 v5, 2, v1
	v_add_u32_e32 v14, v9, v14
	v_add3_u32 v10, s0, v4, v5
	v_or_b32_e32 v11, 8, v1
	v_or_b32_e32 v12, 16, v1
	v_or_b32_e32 v13, 24, v1
	s_lshl_b32 s12, s6, 5
	s_lshl_b32 s13, s7, 5
	v_lshlrev_b32_e32 v4, 2, v2
	v_mov_b32_e32 v5, v3
	v_lshlrev_b32_e32 v6, 2, v6
	v_mov_b32_e32 v7, v3
	v_lshlrev_b32_e32 v8, 1, v8
	v_mov_b32_e32 v9, v3
	v_add_u32_e32 v15, 0x400, v14
	v_add_u32_e32 v16, 0x800, v14
	v_add_u32_e32 v17, 0xc00, v14
	v_add_u32_e32 v18, 0x1000, v14
	v_add_u32_e32 v19, 0x1400, v14
	v_add_u32_e32 v20, 0x1800, v14
	v_add_u32_e32 v21, 0x1c00, v14
.Lp9x_decode:
	s_add_i32 s0, s6, 0xf800
	s_and_b32 s0, s0, 0xffc0
	s_and_b32 s1, s12, 0x7e0
	s_lshl_b32 s2, s0, 13
	v_readlane_b32 s62, v241, 51
	v_readlane_b32 s63, v241, 52
	s_add_u32 s2, s62, s2
	s_addc_u32 s3, s63, 0
	s_lshl_b32 s4, s1, 2
	s_add_u32 s4, s2, s4
	s_addc_u32 s5, s3, 0
	s_mulk_i32 s1, 0x2c00
	s_add_u32 s1, s22, s1
	s_addc_u32 s3, s23, 0
	s_lshl_b32 s0, s0, 1
	s_add_u32 s2, s1, s0
	s_addc_u32 s3, s3, 0
	s_mov_b64 s[0:1], 0x1600
	v_lshl_add_u64 v[22:23], s[4:5], 0, v[4:5]
	v_lshl_add_u64 v[22:23], v[22:23], 0, v[6:7]
	v_add_co_u32_e32 v24, vcc, 0x4000, v22
	s_add_i32 s6, s6, s7
	s_nop 0
	v_addc_co_u32_e32 v25, vcc, 0, v23, vcc
	v_add_co_u32_e32 v26, vcc, 0x8000, v22
	s_add_i32 s12, s12, s13
	s_nop 0
	v_addc_co_u32_e32 v27, vcc, 0, v23, vcc
	v_add_co_u32_e32 v28, vcc, 0xc000, v22
	s_cmpk_lt_i32 s6, 0x1e00
	s_nop 0
	v_addc_co_u32_e32 v29, vcc, 0, v23, vcc
	v_add_co_u32_e32 v30, vcc, 0x10000, v22
	s_nop 1
	v_addc_co_u32_e32 v31, vcc, 0, v23, vcc
	v_add_co_u32_e32 v32, vcc, 0x14000, v22
	s_nop 1
	v_addc_co_u32_e32 v33, vcc, 0, v23, vcc
	v_add_co_u32_e32 v34, vcc, 0x18000, v22
	s_nop 1
	v_addc_co_u32_e32 v35, vcc, 0, v23, vcc
	v_add_co_u32_e32 v36, vcc, 0x1c000, v22
	s_nop 1
	v_addc_co_u32_e32 v37, vcc, 0, v23, vcc
	global_load_dword v2, v[22:23], off nt
	global_load_dword v40, v[24:25], off nt
	global_load_dword v41, v[26:27], off nt
	global_load_dword v42, v[28:29], off nt
	global_load_dword v43, v[30:31], off nt
	global_load_dword v44, v[32:33], off nt
	global_load_dword v45, v[34:35], off nt
	global_load_dword v46, v[36:37], off nt
	v_add_co_u32_e32 v24, vcc, 0x20000, v22
	s_nop 1
	v_addc_co_u32_e32 v25, vcc, 0, v23, vcc
	v_add_co_u32_e32 v26, vcc, 0x24000, v22
	s_nop 1
	v_addc_co_u32_e32 v27, vcc, 0, v23, vcc
	v_add_co_u32_e32 v28, vcc, 0x28000, v22
	s_nop 1
	v_addc_co_u32_e32 v29, vcc, 0, v23, vcc
	v_add_co_u32_e32 v30, vcc, 0x2c000, v22
	s_nop 1
	v_addc_co_u32_e32 v31, vcc, 0, v23, vcc
	v_add_co_u32_e32 v32, vcc, 0x30000, v22
	s_nop 1
	v_addc_co_u32_e32 v33, vcc, 0, v23, vcc
	v_add_co_u32_e32 v34, vcc, 0x34000, v22
	s_nop 1
	v_addc_co_u32_e32 v35, vcc, 0, v23, vcc
	v_add_co_u32_e32 v36, vcc, 0x38000, v22
	s_nop 1
	v_addc_co_u32_e32 v37, vcc, 0, v23, vcc
	v_add_co_u32_e32 v38, vcc, 0x3c000, v22
	s_nop 1
	v_addc_co_u32_e32 v39, vcc, 0, v23, vcc
	global_load_dword v47, v[24:25], off nt
	global_load_dword v48, v[26:27], off nt
	global_load_dword v49, v[28:29], off nt
	global_load_dword v50, v[30:31], off nt
	global_load_dword v51, v[32:33], off nt
	global_load_dword v52, v[34:35], off nt
	global_load_dword v53, v[36:37], off nt
	global_load_dword v54, v[38:39], off nt
	v_add_co_u32_e32 v24, vcc, 0x40000, v22
	s_nop 1
	v_addc_co_u32_e32 v25, vcc, 0, v23, vcc
	v_add_co_u32_e32 v26, vcc, 0x44000, v22
	s_nop 1
	v_addc_co_u32_e32 v27, vcc, 0, v23, vcc
	v_add_co_u32_e32 v28, vcc, 0x48000, v22
	s_nop 1
	v_addc_co_u32_e32 v29, vcc, 0, v23, vcc
	v_add_co_u32_e32 v30, vcc, 0x4c000, v22
	s_nop 1
	v_addc_co_u32_e32 v31, vcc, 0, v23, vcc
	v_add_co_u32_e32 v32, vcc, 0x50000, v22
	s_nop 1
	v_addc_co_u32_e32 v33, vcc, 0, v23, vcc
	v_add_co_u32_e32 v34, vcc, 0x54000, v22
	s_nop 1
	v_addc_co_u32_e32 v35, vcc, 0, v23, vcc
	v_add_co_u32_e32 v36, vcc, 0x58000, v22
	s_nop 1
	v_addc_co_u32_e32 v37, vcc, 0, v23, vcc
	v_add_co_u32_e32 v38, vcc, 0x5c000, v22
	s_nop 1
	v_addc_co_u32_e32 v39, vcc, 0, v23, vcc
	global_load_dword v55, v[24:25], off nt
	global_load_dword v56, v[26:27], off nt
	global_load_dword v57, v[28:29], off nt
	global_load_dword v58, v[30:31], off nt
	global_load_dword v59, v[32:33], off nt
	global_load_dword v60, v[34:35], off nt
	global_load_dword v61, v[36:37], off nt
	s_nop 0
	global_load_dword v38, v[38:39], off nt
	v_add_co_u32_e32 v24, vcc, 0x60000, v22
	s_nop 1
	v_addc_co_u32_e32 v25, vcc, 0, v23, vcc
	v_add_co_u32_e32 v26, vcc, 0x64000, v22
	s_nop 1
	v_addc_co_u32_e32 v27, vcc, 0, v23, vcc
	v_add_co_u32_e32 v28, vcc, 0x68000, v22
	s_nop 1
	v_addc_co_u32_e32 v29, vcc, 0, v23, vcc
	v_add_co_u32_e32 v30, vcc, 0x6c000, v22
	s_nop 1
	v_addc_co_u32_e32 v31, vcc, 0, v23, vcc
	v_add_co_u32_e32 v32, vcc, 0x70000, v22
	s_nop 1
	v_addc_co_u32_e32 v33, vcc, 0, v23, vcc
	v_add_co_u32_e32 v34, vcc, 0x74000, v22
	s_nop 1
	v_addc_co_u32_e32 v35, vcc, 0, v23, vcc
	v_add_co_u32_e32 v36, vcc, 0x78000, v22
	s_nop 1
	v_addc_co_u32_e32 v37, vcc, 0, v23, vcc
	v_add_co_u32_e32 v22, vcc, 0x7c000, v22
	s_nop 1
	v_addc_co_u32_e32 v23, vcc, 0, v23, vcc
	global_load_dword v24, v[24:25], off nt
	s_nop 0
	global_load_dword v25, v[26:27], off nt
	s_nop 0
	global_load_dword v26, v[28:29], off nt
	global_load_dword v27, v[30:31], off nt
	s_nop 0
	global_load_dword v28, v[32:33], off nt
	global_load_dword v29, v[34:35], off nt
	global_load_dword v30, v[36:37], off nt
	s_nop 0
	global_load_dword v22, v[22:23], off nt
	s_waitcnt vmcnt(0)
	ds_write2_b32 v14, v2, v40 offset1:66
	ds_write2_b32 v14, v41, v42 offset0:132 offset1:198
	ds_write2_b32 v15, v43, v44 offset0:8 offset1:74
	ds_write2_b32 v15, v45, v46 offset0:140 offset1:206
	ds_write2_b32 v16, v47, v48 offset0:16 offset1:82
	ds_write2_b32 v16, v49, v50 offset0:148 offset1:214
	ds_write2_b32 v17, v51, v52 offset0:24 offset1:90
	ds_write2_b32 v17, v53, v54 offset0:156 offset1:222
	ds_write2_b32 v18, v55, v56 offset0:32 offset1:98
	ds_write2_b32 v18, v57, v58 offset0:164 offset1:230
	ds_write2_b32 v19, v59, v60 offset0:40 offset1:106
	ds_write2_b32 v19, v61, v38 offset0:172 offset1:238
	ds_write2_b32 v20, v24, v25 offset0:48 offset1:114
	ds_write2_b32 v20, v26, v27 offset0:180 offset1:246
	ds_write2_b32 v21, v28, v29 offset0:56 offset1:122
	ds_write2_b32 v21, v30, v22 offset0:188 offset1:254
	s_waitcnt lgkmcnt(0)
	ds_read2_b32 v[22:23], v10 offset1:33
	s_waitcnt lgkmcnt(0)
	v_cvt_pk_bf16_f32 v22, v22, v23
	ds_read2_b32 v[24:25], v10 offset0:66 offset1:99
	v_mul_u32_u24_e32 v2, s0, v1
	s_waitcnt lgkmcnt(0)
	v_cvt_pk_bf16_f32 v23, v24, v25
	ds_read2_b32 v[24:25], v10 offset0:132 offset1:165
	v_lshl_add_u64 v[28:29], s[2:3], 0, v[8:9]
	v_lshlrev_b32_e32 v2, 1, v2
	s_waitcnt lgkmcnt(0)
	v_cvt_pk_bf16_f32 v24, v24, v25
	ds_read2_b32 v[26:27], v10 offset0:198 offset1:231
	s_waitcnt lgkmcnt(0)
	v_cvt_pk_bf16_f32 v25, v26, v27
	v_lshl_add_u64 v[30:31], v[28:29], 0, v[2:3]
	ds_read2_b32 v[26:27], v10 offset0:8 offset1:41
	global_store_dwordx4 v[30:31], v[22:25], off
	v_mul_u32_u24_e32 v2, s0, v11
	v_lshlrev_b32_e32 v2, 1, v2
	s_waitcnt lgkmcnt(0)
	v_cvt_pk_bf16_f32 v22, v26, v27
	ds_read2_b32 v[24:25], v10 offset0:74 offset1:107
	s_waitcnt lgkmcnt(0)
	v_cvt_pk_bf16_f32 v23, v24, v25
	ds_read2_b32 v[24:25], v10 offset0:140 offset1:173
	s_waitcnt lgkmcnt(0)
	v_cvt_pk_bf16_f32 v24, v24, v25
	ds_read2_b32 v[26:27], v10 offset0:206 offset1:239
	s_waitcnt lgkmcnt(0)
	v_cvt_pk_bf16_f32 v25, v26, v27
	v_lshl_add_u64 v[30:31], v[28:29], 0, v[2:3]
	ds_read2_b32 v[26:27], v10 offset0:16 offset1:49
	global_store_dwordx4 v[30:31], v[22:25], off
	v_mul_u32_u24_e32 v2, s0, v12
	v_lshlrev_b32_e32 v2, 1, v2
	s_waitcnt lgkmcnt(0)
	v_cvt_pk_bf16_f32 v22, v26, v27
	ds_read2_b32 v[24:25], v10 offset0:82 offset1:115
	s_waitcnt lgkmcnt(0)
	v_cvt_pk_bf16_f32 v23, v24, v25
	ds_read2_b32 v[24:25], v10 offset0:148 offset1:181
	s_waitcnt lgkmcnt(0)
	v_cvt_pk_bf16_f32 v24, v24, v25
	ds_read2_b32 v[26:27], v10 offset0:214 offset1:247
	s_waitcnt lgkmcnt(0)
	v_cvt_pk_bf16_f32 v25, v26, v27
	v_lshl_add_u64 v[30:31], v[28:29], 0, v[2:3]
	ds_read2_b32 v[26:27], v10 offset0:24 offset1:57
	global_store_dwordx4 v[30:31], v[22:25], off
	v_mul_u32_u24_e32 v2, s0, v13
	v_lshlrev_b32_e32 v2, 1, v2
	s_waitcnt lgkmcnt(0)
	v_cvt_pk_bf16_f32 v22, v26, v27
	ds_read2_b32 v[24:25], v10 offset0:90 offset1:123
	s_waitcnt lgkmcnt(0)
	v_cvt_pk_bf16_f32 v23, v24, v25
	ds_read2_b32 v[24:25], v10 offset0:156 offset1:189
	s_waitcnt lgkmcnt(0)
	v_cvt_pk_bf16_f32 v24, v24, v25
	ds_read2_b32 v[26:27], v10 offset0:222 offset1:255
	s_waitcnt lgkmcnt(0)
	v_cvt_pk_bf16_f32 v25, v26, v27
	v_lshl_add_u64 v[26:27], v[28:29], 0, v[2:3]
	global_store_dwordx4 v[26:27], v[22:25], off
	s_waitcnt lgkmcnt(0)
	s_cbranch_scc1 .Lp9x_decode
.Lp9x_restore:
	s_mov_b32 s2, s98
	s_mov_b32 s3, s99
	s_mov_b32 s23, s100
.Lp9x_done:
.LBB0_834:
	s_cmp_gt_i32 s91, 10
	s_cselect_b64 s[0:1], -1, 0
	s_and_b64 s[2:3], s[2:3], s[0:1]
	s_andn2_b64 vcc, exec, s[2:3]
	s_cbranch_vccnz .LBB0_888
	s_waitcnt vmcnt(0)
	s_waitcnt vmcnt(0) lgkmcnt(0)
	s_barrier
	s_mov_b64 s[2:3], exec
	v_readlane_b32 s4, v241, 3
	v_readlane_b32 s5, v241, 4
	s_and_b64 s[4:5], s[2:3], s[4:5]
	s_mov_b64 exec, s[4:5]
	s_cbranch_execz .LBB0_887
	s_mov_b32 s4, 0x20c00
	s_addk_i32 s4, 0x100
	v_mov_b32_e32 v0, s4
	s_mov_b32 s4, 0x20c04
	s_waitcnt vmcnt(0) expcnt(0) lgkmcnt(0)
	ds_read_b32 v2, v0
	s_addk_i32 s4, 0x100
	v_mov_b32_e32 v0, s4
	ds_read_b32 v0, v0
	s_waitcnt lgkmcnt(1)
	v_cmp_ne_u32_e32 vcc, 0, v2
	s_cbranch_vccnz .LBB0_851
	v_readlane_b32 s4, v241, 0
	v_readlane_b32 s5, v241, 1
	v_readlane_b32 s6, v241, 2
	s_mul_i32 s18, s5, s6
	s_mul_i32 s18, s18, s4
	s_add_u32 s4, s94, 0x1000
	s_addc_u32 s5, s95, 0
	s_add_u32 s6, s94, 0x1100
	s_addc_u32 s7, s95, 0
	s_add_u32 s8, s94, 0x1200
	s_addc_u32 s9, s95, 0
	s_add_u32 s10, s94, 0x1300
	s_addc_u32 s11, s95, 0
	s_mov_b32 s19, 1
	v_mov_b32_e32 v16, 0
	s_branch .LBB0_839
